# grid barrier second level flattened: leader adds to cross-XCD counter without ticket, every workgroup polls that counter; acquire on arrival
# speedup vs baseline: 1.0314x; 1.0048x over previous
.LBB0_10:
	s_or_b64 exec, exec, s[4:5]
	v_readlane_b32 s6, v252, 2
	s_cmpk_lt_i32 s6, 0x100
	s_cselect_b64 s[0:1], -1, 0
	v_writelane_b32 v252, s0, 11
	s_movk_i32 s64, 0x90
	s_mov_b32 s70, -2.0
	v_writelane_b32 v252, s1, 12
	s_and_b32 s0, s6, 7
	s_lshl_b32 s4, s0, 6
	s_cmpk_gt_i32 s97, 0x7f
	s_cselect_b64 s[8:9], -1, 0
	s_lshl_b32 s1, s97, 1
	s_and_b32 s1, s1, 14
	s_bfe_u32 s3, s97, 0x10006
	s_or_b32 s1, s1, s3
	s_or_b32 s3, s1, 0x90
	v_writelane_b32 v252, s8, 13
	s_cmpk_lt_i32 s97, 0x80
	s_cselect_b32 s3, s1, s3
	v_writelane_b32 v252, s9, 14
	s_cselect_b32 s5, s64, 0x100
	s_or_b32 s1, s4, 0xfffffa00
	v_writelane_b32 v252, s1, 15
	v_writelane_b32 v252, s4, 16
	s_or_b32 s1, s4, 0xfffff600
	v_writelane_b32 v252, s1, 17
	s_lshl_b32 s1, s3, 6
	s_and_b32 s4, s1, 0x7c0
	v_writelane_b32 v252, s4, 18
	s_and_b32 s4, s1, 0x2000
	v_writelane_b32 v252, s4, 19
	v_writelane_b32 v252, s3, 20
	s_cmp_lt_u32 s3, s5
	v_writelane_b32 v252, s5, 21
	s_cselect_b64 s[4:5], -1, 0
	v_writelane_b32 v252, s4, 22
	s_lshl_b32 s3, s0, 9
	s_mov_b32 s88, 0xc1000000
	v_writelane_b32 v252, s5, 23
	v_writelane_b32 v252, s3, 24
	s_lshl_b32 s3, s0, 7
	v_writelane_b32 v252, s3, 25
	s_add_i32 s3, s97, 0xffffff80
	s_add_i32 s4, s87, 0xffffff80
	v_writelane_b32 v252, s4, 26
	s_cmpk_lt_u32 s3, 0x100
	v_writelane_b32 v252, s3, 27
	s_cselect_b64 s[4:5], -1, 0
	v_writelane_b32 v252, s4, 28
	s_mul_i32 s3, s97, 7
	s_mov_b32 s92, 0xc1200000
	v_writelane_b32 v252, s5, 29
	s_mov_b32 s44, 0xc1800000
	v_readlane_b32 s7, v252, 3
	s_add_i32 s24, s7, s3
	s_mul_i32 s3, s7, 0x2400
	s_add_i32 s4, s24, -1
	s_add_i32 s3, s3, 0
	s_cmpk_gt_i32 s24, 0x680
	v_writelane_b32 v252, s3, 30
	s_cselect_b64 s[8:9], -1, 0
	s_add_i32 s3, s24, 0xfffff97f
	s_lshr_b32 s50, s3, 4
	v_writelane_b32 v252, s8, 31
	s_cmp_gt_u32 s3, 31
	s_mov_b32 s12, 0x41000000
	v_writelane_b32 v252, s9, 32
	s_cselect_b64 s[8:9], -1, 0
	v_writelane_b32 v252, s8, 33
	s_lshl_b32 s3, s3, 13
	s_and_b32 s3, s3, 0x20000
	v_writelane_b32 v252, s9, 34
	v_writelane_b32 v252, s3, 35
	s_lshl_b64 s[8:9], s[50:51], 16
	v_writelane_b32 v252, s8, 36
	s_and_b32 s3, s4, 15
	s_mov_b32 s14, 0x41200000
	v_writelane_b32 v252, s9, 37
	v_writelane_b32 v252, s4, 38
	v_writelane_b32 v252, s3, 39
	s_ashr_i32 s4, s97, 1
	s_lshl_b32 s3, s97, 5
	s_and_b32 s3, s3, 32
	s_lshl_b32 s8, s4, 6
	s_cmp_gt_i32 s4, 31
	v_writelane_b32 v252, s3, 40
	s_cselect_b64 s[10:11], -1, 0
	v_writelane_b32 v252, s10, 41
	s_add_i32 s50, s8, 0xfffff800
	s_ashr_i32 s9, s8, 31
	v_writelane_b32 v252, s11, 42
	v_writelane_b32 v252, s50, 43
	s_ashr_i32 s5, s4, 31
	s_lshl_b64 s[4:5], s[4:5], 19
	v_writelane_b32 v252, s51, 44
	v_writelane_b32 v252, s8, 45
	s_cmpk_lt_i32 s97, 0x300
	s_mov_b32 s16, 0x41800000
	v_writelane_b32 v252, s9, 46
	v_writelane_b32 v252, s4, 47
	s_mov_b32 s18, 0x41900000
	s_mov_b32 s20, 0x41c00000
	v_writelane_b32 v252, s5, 48
	s_cselect_b64 s[4:5], -1, 0
	v_writelane_b32 v252, s4, 49
	s_ashr_i32 s3, s97, 31
	s_lshl_b32 s80, s87, 3
	v_writelane_b32 v252, s5, 50
	v_writelane_b32 v252, s3, 51
	s_lshr_b32 s3, s3, 29
	s_ashr_i32 s5, s87, 31
	s_add_i32 s4, s97, s3
	v_writelane_b32 v252, s5, 52
	s_lshl_b32 s5, s6, 3
	s_ashr_i32 s3, s4, 3
	s_and_b32 s4, s4, -8
	v_writelane_b32 v252, s5, 53
	s_add_i32 s6, s5, s7
	s_lshl_b32 s5, s7, 14
	s_sub_i32 s4, s97, s4
	s_add_i32 s5, s5, 0
	s_cmpk_lt_i32 s6, 0x6c0
	v_writelane_b32 v252, s5, 54
	s_cselect_b64 s[8:9], -1, 0
	v_writelane_b32 v252, s8, 55
	s_cmpk_lt_i32 s6, 0x680
	s_mov_b32 s22, 0x41d00000
	v_writelane_b32 v252, s9, 56
	s_cselect_b64 s[8:9], -1, 0
	v_writelane_b32 v252, s8, 57
	s_cmpk_gt_i32 s6, 0x67f
	v_mov_b32_e32 v0, 0
	v_writelane_b32 v252, s9, 58
	s_cselect_b64 s[8:9], -1, 0
	s_add_i32 s5, s6, 0xfffff980
	s_lshr_b32 s50, s5, 4
	v_writelane_b32 v252, s8, 59
	s_cmp_gt_u32 s5, 31
	v_mov_b32_e32 v220, 0x358637bd
	v_writelane_b32 v252, s9, 60
	s_cselect_b64 s[8:9], -1, 0
	v_writelane_b32 v252, s8, 61
	s_lshl_b32 s5, s5, 13
	s_and_b32 s5, s5, 0x20000
	v_writelane_b32 v252, s9, 62
	s_lshl_b64 s[8:9], s[50:51], 16
	v_writelane_b32 v253, s8, 0
	v_writelane_b32 v252, s5, 63
	s_and_b32 s5, s6, 15
	v_writelane_b32 v253, s9, 1
	v_writelane_b32 v253, s6, 2
	s_cmpk_lt_i32 s97, 0x100
	v_writelane_b32 v253, s5, 3
	s_cselect_b64 s[6:7], -1, 0
	s_lshl_b32 s5, s4, 5
	v_writelane_b32 v253, s6, 4
	s_cmpk_lt_i32 s97, 0x400
	v_mov_b32_e32 v221, 0x3a27c5ac
	v_writelane_b32 v253, s7, 5
	s_cselect_b64 s[6:7], -1, 0
	v_writelane_b32 v253, s6, 6
	v_mov_b32_e32 v222, 0x260
	v_mov_b32_e32 v223, 1
	v_writelane_b32 v253, s7, 7
	s_lshl_b32 s6, s4, 7
	s_cmp_eq_u32 s2, 15
	s_cselect_b64 s[8:9], -1, 0
	v_writelane_b32 v253, s8, 8
	s_cmp_eq_u32 s2, 14
	s_mov_b32 s71, 0xc0400000
	v_writelane_b32 v253, s9, 9
	s_cselect_b64 s[8:9], -1, 0
	v_writelane_b32 v253, s8, 10
	s_cmp_eq_u32 s2, 13
	s_mov_b32 s89, 0xc1100000
	v_writelane_b32 v253, s9, 11
	s_cselect_b64 s[8:9], -1, 0
	v_writelane_b32 v253, s8, 12
	s_cmp_eq_u32 s2, 12
	s_mov_b32 s93, 0xc1300000
	v_writelane_b32 v253, s9, 13
	s_cselect_b64 s[8:9], -1, 0
	v_writelane_b32 v253, s8, 14
	s_cmp_eq_u32 s2, 11
	s_mov_b32 s45, 0xc1880000
	v_writelane_b32 v253, s9, 15
	s_cselect_b64 s[8:9], -1, 0
	v_writelane_b32 v253, s8, 16
	s_cmp_eq_u32 s2, 10
	s_mov_b32 s13, 0x41100000
	v_writelane_b32 v253, s9, 17
	s_cselect_b64 s[8:9], -1, 0
	v_writelane_b32 v253, s8, 18
	s_cmp_eq_u32 s2, 9
	s_mov_b32 s15, 0x41300000
	v_writelane_b32 v253, s9, 19
	s_cselect_b64 s[8:9], -1, 0
	v_writelane_b32 v253, s8, 20
	s_cmp_eq_u32 s2, 8
	s_mov_b32 s17, 0x41880000
	v_writelane_b32 v253, s9, 21
	s_cselect_b64 s[8:9], -1, 0
	v_writelane_b32 v253, s8, 22
	s_cmp_eq_u32 s2, 7
	s_mov_b32 s19, 0x41980000
	v_writelane_b32 v253, s9, 23
	s_cselect_b64 s[8:9], -1, 0
	v_writelane_b32 v253, s8, 24
	s_cmp_eq_u32 s2, 6
	s_mov_b32 s21, 0x41c80000
	v_writelane_b32 v253, s9, 25
	s_cselect_b64 s[8:9], -1, 0
	v_writelane_b32 v253, s8, 26
	s_cmp_eq_u32 s2, 5
	s_mov_b32 s23, 0x41d80000
	v_writelane_b32 v253, s9, 27
	s_cselect_b64 s[8:9], -1, 0
	v_writelane_b32 v253, s8, 28
	s_cmp_eq_u32 s2, 4
	v_mov_b32_e32 v224, 0x3f80
	v_writelane_b32 v253, s9, 29
	s_cselect_b64 s[8:9], -1, 0
	v_writelane_b32 v253, s8, 30
	s_cmp_eq_u32 s2, 3
	v_mov_b32_e32 v225, 0xfff
	v_writelane_b32 v253, s9, 31
	s_cselect_b64 s[8:9], -1, 0
	v_writelane_b32 v253, s8, 32
	s_cmp_eq_u32 s2, 2
	v_mov_b32_e32 v226, 0xf149f2ca
	v_writelane_b32 v253, s9, 33
	s_cselect_b64 s[8:9], -1, 0
	v_writelane_b32 v253, s8, 34
	s_cmp_eq_u32 s2, 1
	v_mov_b64_e32 v[194:195], 0x2ff
	v_writelane_b32 v253, s9, 35
	s_cselect_b64 s[8:9], -1, 0
	v_writelane_b32 v253, s8, 36
	s_cmp_eq_u32 s2, 0
	s_mul_i32 s2, s4, 33
	v_writelane_b32 v253, s9, 37
	s_cselect_b64 s[8:9], -1, 0
	s_cmp_lt_i32 s4, 0
	s_cselect_b32 s2, s2, s5
	s_movk_i32 s5, 0x61
	s_cselect_b32 s5, s5, 0x60
	s_mul_i32 s5, s4, s5
	s_mulk_i32 s4, 0x81
	s_cselect_b32 s4, s4, s6
	s_add_i32 s5, s5, s3
	s_mul_hi_i32 s6, s5, 0x2aaaaaab
	s_lshr_b32 s7, s6, 31
	s_ashr_i32 s6, s6, 4
	s_add_i32 s6, s6, s7
	s_mul_i32 s7, s6, 0x60
	s_sub_i32 s5, s5, s7
	s_bfe_i32 s7, s5, 0x80000
	s_bfe_u32 s7, s7, 0x3000c
	v_writelane_b32 v253, s8, 38
	s_add_i32 s7, s5, s7
	s_add_i32 s2, s2, s3
	v_writelane_b32 v253, s9, 39
	s_and_b32 s8, s7, 0xf8
	s_sub_i32 s5, s5, s8
	s_ashr_i32 s8, s2, 31
	s_lshr_b32 s8, s8, 27
	s_add_i32 s8, s2, s8
	s_and_b32 s9, s8, 0xffe0
	s_sub_i32 s2, s2, s9
	s_bfe_i32 s9, s2, 0x80000
	s_add_i32 s3, s4, s3
	s_bfe_u32 s9, s9, 0x3000c
	s_ashr_i32 s4, s3, 31
	s_add_i32 s9, s2, s9
	s_lshr_b32 s4, s4, 25
	s_and_b32 s10, s9, 0xf8
	s_add_i32 s4, s3, s4
	s_sub_i32 s2, s2, s10
	s_and_b32 s10, s4, 0xff80
	s_sub_i32 s3, s3, s10
	s_bfe_i32 s10, s3, 0x80000
	s_bfe_u32 s10, s10, 0x3000c
	s_lshl_b32 s6, s6, 3
	s_sext_i32_i8 s5, s5
	s_add_i32 s10, s3, s10
	s_add_i32 s26, s6, s5
	s_ashr_i32 s5, s8, 5
	s_and_b32 s11, s10, 0xf8
	s_lshl_b32 s5, s5, 3
	s_sext_i32_i8 s2, s2
	s_sub_i32 s3, s3, s11
	s_add_i32 s8, s5, s2
	s_ashr_i32 s2, s4, 7
	s_bfe_i32 s4, s10, 0x80000
	s_lshl_b32 s2, s2, 3
	s_sext_i32_i16 s4, s4
	s_sext_i32_i8 s3, s3
	s_add_i32 s28, s2, s3
	s_ashr_i32 s2, s4, 3
	v_writelane_b32 v253, s2, 40
	s_lshr_b32 s2, s4, 3
	s_bfe_i64 s[2:3], s[2:3], 0x100000
	s_bfe_i32 s7, s7, 0x80000
	s_lshl_b64 s[2:3], s[2:3], 19
	s_sext_i32_i16 s7, s7
	v_writelane_b32 v253, s2, 41
	s_bfe_i32 s6, s9, 0x80000
	s_ashr_i32 s9, s8, 31
	v_writelane_b32 v253, s3, 42
	s_ashr_i32 s2, s7, 3
	v_writelane_b32 v253, s2, 43
	s_lshr_b32 s2, s7, 3
	s_bfe_i64 s[2:3], s[2:3], 0x100000
	s_lshl_b64 s[2:3], s[2:3], 19
	v_writelane_b32 v253, s2, 44
	s_sext_i32_i16 s6, s6
	s_addk_i32 s1, 0x400
	v_writelane_b32 v253, s3, 45
	v_writelane_b32 v253, s8, 46
	s_ashr_i32 s2, s6, 3
	s_lshl_b32 s0, s0, 2
	v_writelane_b32 v253, s9, 47
	v_writelane_b32 v253, s2, 48
	s_lshr_b32 s2, s6, 3
	s_bfe_i64 s[2:3], s[2:3], 0x100000
	v_writelane_b32 v253, s2, 49
	s_ashr_i32 s29, s28, 31
	s_ashr_i32 s27, s26, 31
	v_writelane_b32 v253, s3, 50
	v_writelane_b32 v253, s1, 51
	s_lshl_b32 s1, s97, 6
	s_addk_i32 s1, 0xe000
	v_writelane_b32 v253, s1, 52
	s_lshl_b32 s1, s87, 6
	s_addk_i32 s1, 0xe000
	v_writelane_b32 v253, s1, 53
	v_writelane_b32 v253, s0, 54
	s_lshl_b32 s1, s97, 10
	v_writelane_b32 v253, s24, 55
	s_add_i32 s0, s24, 0xfffffcff
	s_and_b32 s1, s1, 0x400
	v_writelane_b32 v253, s0, 56
	v_writelane_b32 v253, s1, 57
	s_or_b32 s0, s1, 0x800
	v_writelane_b32 v253, s0, 58
	s_lshl_b32 s0, s87, 4
	v_writelane_b32 v253, s0, 59
	s_add_i32 s0, 0, 0x4400
	v_writelane_b32 v253, s0, 60
	s_add_i32 s0, 0, 0x1f800
	v_writelane_b32 v253, s0, 61
	s_add_i32 s0, 0, 0x21c00
	v_writelane_b32 v253, s0, 62
	s_add_i32 s0, 0, 0x25200
	v_writelane_b32 v253, s0, 63
	s_add_i32 s0, 0, 0x25300
	v_writelane_b32 v254, s0, 0
	s_add_i32 s0, 0, 0x26160
	v_writelane_b32 v254, s0, 1
	s_add_i32 s0, 0, 0x26164
	v_writelane_b32 v254, s0, 2
	s_add_i32 s0, 0, 0x1400
	v_writelane_b32 v254, s0, 3
	s_add_i32 s0, 0, 0x1800
	v_writelane_b32 v254, s0, 4
	s_add_i32 s0, 0, 0x2800
	v_writelane_b32 v254, s0, 5
	s_add_i32 s0, 0, 0x2c00
	v_writelane_b32 v254, s0, 6
	s_add_i32 s0, 0, 0x3400
	v_writelane_b32 v254, s0, 7
	s_add_i32 s0, 0, 0x3800
	v_writelane_b32 v254, s0, 8
	s_add_i32 s0, 0, 0x3c00
	v_writelane_b32 v254, s0, 9
	s_add_i32 s0, 0, 0x4800
	v_writelane_b32 v254, s0, 10
	s_add_i32 s0, 0, 0x4c00
	v_writelane_b32 v254, s0, 11
	s_add_i32 s0, 0, 0x5000
	v_writelane_b32 v254, s0, 12
	s_add_i32 s0, 0, 0x5400
	v_writelane_b32 v254, s0, 13
	s_add_i32 s0, 0, 0x5800
	v_writelane_b32 v254, s0, 14
	s_add_i32 s0, 0, 0x5c00
	v_writelane_b32 v254, s0, 15
	s_add_i32 s0, 0, 0x6400
	v_writelane_b32 v254, s0, 16
	s_add_i32 s0, 0, 0x6800
	v_writelane_b32 v254, s0, 17
	s_add_i32 s0, 0, 0x6c00
	v_writelane_b32 v254, s0, 18
	s_add_i32 s0, 0, 0x7000
	v_writelane_b32 v254, s0, 19
	s_add_i32 s0, 0, 0x7400
	v_writelane_b32 v254, s0, 20
	s_add_i32 s0, 0, 0x7800
	v_writelane_b32 v254, s0, 21
	s_add_i32 s0, 0, 0x7c00
	v_writelane_b32 v254, s0, 22
	s_add_i32 s0, 0, 0x8400
	v_writelane_b32 v254, s0, 23
	s_add_i32 s0, 0, 0x8800
	v_writelane_b32 v254, s0, 24
	s_add_i32 s0, 0, 0x8c00
	v_writelane_b32 v254, s0, 25
	s_add_i32 s0, 0, 0x9400
	v_writelane_b32 v254, s0, 26
	s_add_i32 s0, 0, 0x9800
	v_writelane_b32 v254, s0, 27
	s_add_i32 s0, 0, 0x9c00
	v_writelane_b32 v254, s0, 28
	s_add_i32 s0, 0, 0xa400
	v_writelane_b32 v254, s0, 29
	s_add_i32 s0, 0, 0xa800
	v_writelane_b32 v254, s0, 30
	s_add_i32 s0, 0, 0xac00
	v_writelane_b32 v254, s0, 31
	s_add_i32 s0, 0, 0xb000
	v_writelane_b32 v254, s0, 32
	s_add_i32 s0, 0, 0xb800
	v_writelane_b32 v254, s0, 33
	s_add_i32 s0, 0, 0xbc00
	v_writelane_b32 v254, s0, 34
	s_add_i32 s0, 0, 0xc400
	v_writelane_b32 v254, s0, 35
	s_add_i32 s0, 0, 0xc800
	v_writelane_b32 v254, s0, 36
	s_add_i32 s0, 0, 0xcc00
	v_writelane_b32 v254, s0, 37
	s_add_i32 s0, 0, 0xd000
	v_writelane_b32 v254, s0, 38
	s_add_i32 s0, 0, 0xd400
	v_writelane_b32 v254, s0, 39
	s_add_i32 s0, 0, 0xdc00
	v_writelane_b32 v254, s0, 40
	s_add_i32 s0, 0, 0xe400
	v_writelane_b32 v254, s0, 41
	s_add_i32 s0, 0, 0xe800
	v_writelane_b32 v254, s0, 42
	s_add_i32 s0, 0, 0xec00
	v_writelane_b32 v254, s0, 43
	s_lshl_b64 s[0:1], s[28:29], 14
	v_writelane_b32 v254, s0, 44
	s_mov_b32 s4, 0xc1900000
	s_mov_b32 s6, 0xc1c00000
	v_writelane_b32 v254, s1, 45
	s_mov_b32 s0, s28
	v_writelane_b32 v254, s0, 46
	s_mov_b32 s8, 0xc1d00000
	s_mov_b32 s10, 2.0
	v_writelane_b32 v254, s1, 47
	s_lshl_b64 s[0:1], s[28:29], 19
	v_writelane_b32 v254, s0, 48
	s_mov_b32 s5, 0xc1980000
	s_mov_b32 s7, 0xc1c80000
	v_writelane_b32 v254, s1, 49
	s_lshl_b64 s[0:1], s[26:27], 14
	v_writelane_b32 v254, s0, 50
	s_mov_b32 s9, 0xc1d80000
	s_mov_b32 s11, 0x40400000
	v_writelane_b32 v254, s1, 51
	s_mov_b32 s0, s26
	v_writelane_b32 v254, s0, 52
	v_mov_b32_e32 v227, 0x3e38aa3b
	s_mov_b32 s65, 0x5040100
	v_writelane_b32 v254, s1, 53
	s_lshl_b64 s[0:1], s[26:27], 19
	v_writelane_b32 v254, s0, 54
	s_mov_b32 s33, 0x42800000
	s_movk_i32 s2, 0x7fff
	v_writelane_b32 v254, s1, 55
	s_mov_b64 s[0:1], 0
	v_writelane_b32 v254, s0, 56
	s_mov_b64 s[34:35], 0x80
	s_mov_b64 s[74:75], 0x1100
	v_writelane_b32 v254, s1, 57
	v_writelane_b32 v254, s97, 58
	v_writelane_b32 v254, s94, 59
	s_mov_b32 s86, 0xbf600358
	s_mov_b32 s90, -1.0
	v_writelane_b32 v254, s95, 60
	v_writelane_b32 v254, s87, 61
	v_writelane_b32 v254, s80, 62
	s_branch .LBB0_14
.LBB0_12:
	s_or_b64 exec, exec, s[24:25]
	s_waitcnt lgkmcnt(0)
	s_barrier

.LBB0_860:
	v_readlane_b32 s0, v252, 10
	s_lshl_b32 s50, s0, 2
	v_lshl_add_u64 v[4:5], v[2:3], 0, s[50:51]
	v_add_co_u32_e32 v10, vcc, 0x1000, v4
	v_cvt_f32_u32_e32 v1, v8
	s_nop 0
	v_addc_co_u32_e32 v11, vcc, 0, v5, vcc
	flat_atomic_add v7, v[10:11], v223 offset:1024 sc0
	v_rcp_iflag_f32_e32 v1, v1
	v_sub_u32_e32 v9, 0, v8
	v_mul_f32_e32 v1, 0x4f7ffffe, v1
	v_cvt_u32_f32_e32 v1, v1
	v_mul_lo_u32 v9, v9, v1
	v_mul_hi_u32 v9, v1, v9
	v_add_u32_e32 v1, v1, v9
	s_waitcnt vmcnt(0) lgkmcnt(0)
	v_mul_hi_u32 v1, v7, v1
	v_mul_lo_u32 v9, v1, v8
	v_sub_u32_e32 v9, v7, v9
	v_cmp_ge_u32_e32 vcc, v9, v8
	v_add_u32_e32 v10, 1, v1
	v_add_u32_e32 v7, 1, v7
	v_cndmask_b32_e32 v1, v1, v10, vcc
	v_sub_u32_e32 v10, v9, v8
	v_cndmask_b32_e32 v9, v9, v10, vcc
	v_cmp_ge_u32_e32 vcc, v9, v8
	v_add_u32_e32 v9, 1, v1
	s_nop 0
	v_cndmask_b32_e32 v1, v1, v9, vcc
	v_mad_u64_u32 v[8:9], s[0:1], v8, v1, v[8:9]
	s_mov_b64 s[26:27], 0x3000
	v_add_u32_e32 v9, 1, v1
	v_lshl_add_u64 v[10:11], v[2:3], 0, s[26:27]
	v_mul_lo_u32 v9, v9, v6
	v_cmp_ne_u32_e32 vcc, v7, v8
	s_cbranch_vccnz .Lgb_arrived
	buffer_wbl2 sc1
	buffer_inv sc1
	s_waitcnt vmcnt(0)
	flat_atomic_add v[10:11], v223 offset:1024
	s_branch .Lgb_poll
.Lgb_arrived:
	buffer_inv sc1

.Lgb_spin:
	flat_load_dword v7, v[10:11] offset:1024 sc1
	s_waitcnt vmcnt(0) lgkmcnt(0)
	v_cmp_lt_u32_e32 vcc, v7, v9
	s_cbranch_vccz .Lgb_done
	s_sleep 1
	s_add_i32 s0, s0, 1
	s_and_b32 s1, s0, 0xff
	s_cmp_lg_u32 s1, 0
	s_cbranch_scc1 .Lgb_spin
	flat_load_dword v7, v[2:3] offset:512 sc1
	s_waitcnt vmcnt(0) lgkmcnt(0)
	v_cmp_ne_u32_e32 vcc, 0, v7
	s_cbranch_vccnz .Lgb_done
	s_cmp_lt_u32 s0, 0x40001
	s_cbranch_scc1 .Lgb_spin
	flat_atomic_add v[2:3], v223 offset:512
.Lgb_done:
	s_waitcnt vmcnt(0) lgkmcnt(0)
	s_branch .LBB0_12

.LBB0_887:
	s_mov_b32 s26, 1.0
	v_mov_b32_e32 v14, s26
	s_branch .LBB0_728
.LBB0_892:
	v_mov_b32_e32 v9, 1.0
	v_mov_b32_e32 v8, v9
	v_cndmask_b32_e64 v4, 0, 1, s[38:39]
	v_cmp_ne_u32_e64 s[36:37], 1, v4
	s_andn2_b64 vcc, exec, s[38:39]
	s_cbranch_vccz .LBB0_486
